# PA: the tiles-stored record that PB waits on is published from inside the unit loop once the z/q/k|v tiles (units 0,1) are stored, so neighbouring panel groups no longer wait for each other's gate til
# speedup vs baseline: 1.0122x; 1.0122x over previous
; #define PG8_STAGE(bufoff, gbase, voff) do { _Pragma("unroll") for (int _i = 0; _i < 2; ++_i) \
;         __builtin_amdgcn_global_load_lds((const unsigned*)((const char*)(gbase) + (voff)[_i]), (PG8_LAS unsigned*)(lds + (bufoff) + ldsw + _i * 8192), 16, 0, 0); } while (0)
; #define PG8_LDA(dst, b, h) do { _Pragma("unroll") for (int m = 0; m < 4; ++m) _Pragma("unroll") for (int k = 0; k < 2; ++k) dst[m][k] = *(const PG8_LAS bf16x8*)(lds + PG8_SA(b, h) + aoff + m * 2048 + k * 1024); } while (0)
; #define PG8_LDB(dst, b, h) do { _Pragma("unroll") for (int n = 0; n < 2; ++n) _Pragma("unroll") for (int k = 0; k < 2; ++k) dst[n][k] = *(const PG8_LAS bf16x8*)(lds + PG8_SB(b, h) + boff + n * 2048 + k * 1024); } while (0)
; #define PG8_MMA(ai, bj, At, Bt) do { __builtin_amdgcn_s_setprio(1); _Pragma("unroll") for (int m = 0; m < 4; ++m) _Pragma("unroll") for (int n = 0; n < 2; ++n) _Pragma("unroll") for (int k = 0; k < 2; ++k) \
;         acc[ai][bj][m][n] = __builtin_amdgcn_mfma_f32_16x16x32_bf16(Bt[n][k], At[m][k], acc[ai][bj][m][n], 0, 0, 0); __builtin_amdgcn_s_setprio(0); } while (0)
; #define PG8_WAIT_V(n) asm volatile("s_waitcnt vmcnt(" #n ")" ::: "memory")
; #define PG8_WAIT_L(n) asm volatile("s_waitcnt lgkmcnt(" #n ")" ::: "memory")
; #define PG8_BAR __builtin_amdgcn_s_barrier()
; #define PG8_SCHED __builtin_amdgcn_sched_barrier(0)
; template <class Epi, class Sched, bool ALIGN_EPI = false, bool SP2 = false>
; __device__ __forceinline__ void gemm_phase(PG8_LAS unsigned char* lds, const Gemm g, const Sched& S, const Epi& E) {
;     ...
;             PG8_LDB(B0, 0, 0); PG8_LDB(B1, 0, 1); PG8_SCHED; PG8_LDA(At, 0, 0); PG8_STAGE(PG8_SA(1, 1), a1 + hstep, voffA);
;             PG8_WAIT_V(8); PG8_WAIT_L(0); PG8_BAR; PG8_MMA(0, 0, At, B0); PG8_MMA(0, 1, At, B1); PG8_BAR; PG8_SCHED;
;             PG8_LDA(At, 0, 1); PG8_STAGE(PG8_SB(0, 0), b2, voffB); PG8_STAGE(PG8_SB(0, 1), b2 + hstepB, voffB); PG8_STAGE(PG8_SA(0, 0), a2, voffA);
;             PG8_WAIT_V(8); PG8_WAIT_L(0); PG8_BAR; PG8_MMA(1, 0, At, B0); PG8_MMA(1, 1, At, B1); PG8_BAR; PG8_SCHED;
.LBB0_130:
	s_add_u32 s34, s36, 0xfffc0080
	s_addc_u32 s35, s37, -1
	s_add_i32 s88, 0, 0x10000
	s_cmp_eq_u32 s31, 12
	s_cselect_b32 s75, s49, s35
	s_cselect_b32 s74, s77, s34
	v_add_u32_e32 v150, s88, v141
	s_cselect_b32 s39, s51, s30
	s_cselect_b32 s38, vcc_lo, vcc_hi
	s_add_i32 s89, 0, 0x14000
	ds_read_b128 v[146:149], v150
	ds_read_b128 v[156:159], v150 offset:1024
	ds_read_b128 v[164:167], v150 offset:2048
	ds_read_b128 v[168:171], v150 offset:3072
	v_add_u32_e32 v150, s89, v141
	ds_read_b128 v[172:175], v150
	ds_read_b128 v[176:179], v150 offset:1024
	ds_read_b128 v[180:183], v150 offset:2048
	ds_read_b128 v[184:187], v150 offset:3072
	v_lshl_add_u64 v[150:151], s[36:37], 0, v[142:143]
	s_add_i32 m0, s24, 0xc000
	ds_read_b128 v[188:191], v154
	ds_read_b128 v[204:207], v154 offset:1024
	ds_read_b128 v[208:211], v154 offset:2048
	ds_read_b128 v[212:215], v154 offset:3072
	ds_read_b128 v[216:219], v154 offset:4096
	ds_read_b128 v[220:223], v154 offset:5120
	ds_read_b128 v[224:227], v154 offset:6144
	ds_read_b128 v[228:231], v154 offset:7168
	global_load_lds_dwordx4 v[150:151], off
	v_lshl_add_u64 v[150:151], s[36:37], 0, v[144:145]
	s_add_i32 m0, s24, 0xe000
	s_nop 0
	global_load_lds_dwordx4 v[150:151], off
	s_waitcnt vmcnt(8)
	s_waitcnt lgkmcnt(0)
	s_barrier
	s_setprio 1
	s_waitcnt lgkmcnt(0)
	v_mfma_f32_16x16x32_bf16 v[128:131], v[146:149], v[188:191], v[128:131]
	v_mfma_f32_16x16x32_bf16 v[124:127], v[164:167], v[188:191], v[124:127]
	v_mfma_f32_16x16x32_bf16 v[112:115], v[146:149], v[208:211], v[112:115]
	v_mfma_f32_16x16x32_bf16 v[108:111], v[164:167], v[208:211], v[108:111]
	v_mfma_f32_16x16x32_bf16 v[96:99], v[146:149], v[216:219], v[96:99]
	v_mfma_f32_16x16x32_bf16 v[92:95], v[164:167], v[216:219], v[92:95]
	v_mfma_f32_16x16x32_bf16 v[80:83], v[146:149], v[224:227], v[80:83]
	v_mfma_f32_16x16x32_bf16 v[76:79], v[164:167], v[224:227], v[76:79]
	v_mfma_f32_16x16x32_bf16 v[128:131], v[156:159], v[204:207], v[128:131]
	v_mfma_f32_16x16x32_bf16 v[124:127], v[168:171], v[204:207], v[124:127]
	v_mfma_f32_16x16x32_bf16 v[112:115], v[156:159], v[212:215], v[112:115]
	v_mfma_f32_16x16x32_bf16 v[108:111], v[168:171], v[212:215], v[108:111]
	v_mfma_f32_16x16x32_bf16 v[96:99], v[156:159], v[220:223], v[96:99]
	v_mfma_f32_16x16x32_bf16 v[92:95], v[168:171], v[220:223], v[92:95]
	v_mfma_f32_16x16x32_bf16 v[80:83], v[156:159], v[228:231], v[80:83]
	v_mfma_f32_16x16x32_bf16 v[76:79], v[168:171], v[228:231], v[76:79]
	s_setprio 0
	s_setprio 1
	v_mfma_f32_16x16x32_bf16 v[120:123], v[172:175], v[188:191], v[120:123]
	v_mfma_f32_16x16x32_bf16 v[116:119], v[180:183], v[188:191], v[116:119]
	v_mfma_f32_16x16x32_bf16 v[104:107], v[172:175], v[208:211], v[104:107]
	v_mfma_f32_16x16x32_bf16 v[100:103], v[180:183], v[208:211], v[100:103]
	v_mfma_f32_16x16x32_bf16 v[88:91], v[172:175], v[216:219], v[88:91]
	v_mfma_f32_16x16x32_bf16 v[84:87], v[180:183], v[216:219], v[84:87]
	v_mfma_f32_16x16x32_bf16 v[72:75], v[172:175], v[224:227], v[72:75]
	v_mfma_f32_16x16x32_bf16 v[68:71], v[180:183], v[224:227], v[68:71]
	v_mfma_f32_16x16x32_bf16 v[120:123], v[176:179], v[204:207], v[120:123]
	v_mfma_f32_16x16x32_bf16 v[116:119], v[184:187], v[204:207], v[116:119]
	v_mfma_f32_16x16x32_bf16 v[104:107], v[176:179], v[212:215], v[104:107]
	v_mfma_f32_16x16x32_bf16 v[100:103], v[184:187], v[212:215], v[100:103]
	v_mfma_f32_16x16x32_bf16 v[88:91], v[176:179], v[220:223], v[88:91]
	v_mfma_f32_16x16x32_bf16 v[84:87], v[184:187], v[220:223], v[84:87]
	v_mfma_f32_16x16x32_bf16 v[72:75], v[176:179], v[228:231], v[72:75]
	v_mfma_f32_16x16x32_bf16 v[68:71], v[184:187], v[228:231], v[68:71]
	s_setprio 0
	s_barrier
	s_add_i32 s34, s88, s23
	v_lshl_add_u64 v[150:151], s[38:39], 0, v[136:137]
	s_mov_b32 m0, s34
	ds_read_b128 v[188:191], v154 offset:16384
	ds_read_b128 v[204:207], v154 offset:17408
	ds_read_b128 v[208:211], v154 offset:18432
	ds_read_b128 v[212:215], v154 offset:19456
	ds_read_b128 v[216:219], v154 offset:20480
	ds_read_b128 v[220:223], v154 offset:21504
	ds_read_b128 v[224:227], v154 offset:22528
	ds_read_b128 v[228:231], v154 offset:23552
	global_load_lds_dwordx4 v[150:151], off
	s_add_i32 m0, s34, 0x2000
	s_add_u32 s34, s38, 0x40000
	v_lshl_add_u64 v[192:193], s[38:39], 0, v[132:133]
	s_addc_u32 s35, s39, 0
	s_add_i32 s88, s89, s23
	global_load_lds_dwordx4 v[192:193], off
	v_lshl_add_u64 v[232:233], s[34:35], 0, v[136:137]
	s_mov_b32 m0, s88
	v_lshl_add_u64 v[234:235], s[74:75], 0, v[134:135]
	global_load_lds_dwordx4 v[232:233], off
	v_lshl_add_u64 v[232:233], s[34:35], 0, v[132:133]
	s_add_i32 m0, s88, 0x2000
	s_nop 0
	global_load_lds_dwordx4 v[232:233], off
	v_lshl_add_u64 v[232:233], s[74:75], 0, v[138:139]
	s_mov_b32 m0, s24
	s_nop 0
	global_load_lds_dwordx4 v[232:233], off
	s_mov_b32 m0, s25
	s_nop 0
	global_load_lds_dwordx4 v[234:235], off
	s_waitcnt vmcnt(8)
	s_waitcnt lgkmcnt(0)
	s_barrier
; #define PG8_STAGE(bufoff, gbase, voff) do { _Pragma("unroll") for (int _i = 0; _i < 2; ++_i) \
;         __builtin_amdgcn_global_load_lds((const unsigned*)((const char*)(gbase) + (voff)[_i]), (PG8_LAS unsigned*)(lds + (bufoff) + ldsw + _i * 8192), 16, 0, 0); } while (0)
; #define PG8_LDA(dst, b, h) do { _Pragma("unroll") for (int m = 0; m < 4; ++m) _Pragma("unroll") for (int k = 0; k < 2; ++k) dst[m][k] = *(const PG8_LAS bf16x8*)(lds + PG8_SA(b, h) + aoff + m * 2048 + k * 1024); } while (0)
; #define PG8_LDB(dst, b, h) do { _Pragma("unroll") for (int n = 0; n < 2; ++n) _Pragma("unroll") for (int k = 0; k < 2; ++k) dst[n][k] = *(const PG8_LAS bf16x8*)(lds + PG8_SB(b, h) + boff + n * 2048 + k * 1024); } while (0)
; #define PG8_MMA(ai, bj, At, Bt) do { __builtin_amdgcn_s_setprio(1); _Pragma("unroll") for (int m = 0; m < 4; ++m) _Pragma("unroll") for (int n = 0; n < 2; ++n) _Pragma("unroll") for (int k = 0; k < 2; ++k) \
;         acc[ai][bj][m][n] = __builtin_amdgcn_mfma_f32_16x16x32_bf16(Bt[n][k], At[m][k], acc[ai][bj][m][n], 0, 0, 0); __builtin_amdgcn_s_setprio(0); } while (0)
; #define PG8_WAIT_V(n) asm volatile("s_waitcnt vmcnt(" #n ")" ::: "memory")
; #define PG8_WAIT_L(n) asm volatile("s_waitcnt lgkmcnt(" #n ")" ::: "memory")
; #define PG8_BAR __builtin_amdgcn_s_barrier()
; #define PG8_SCHED __builtin_amdgcn_sched_barrier(0)
; template <class Epi, class Sched, bool ALIGN_EPI = false, bool SP2 = false>
; __device__ __forceinline__ void gemm_phase(PG8_LAS unsigned char* lds, const Gemm g, const Sched& S, const Epi& E) {
;     ...
;             PG8_WAIT_V(8); PG8_WAIT_L(0); PG8_BAR; PG8_MMA(1, 0, At, B0); PG8_MMA(1, 1, At, B1); PG8_BAR; PG8_SCHED;
;             PG8_LDB(B0, 1, 0); PG8_LDB(B1, 1, 1); PG8_SCHED; PG8_LDA(At, 1, 0); PG8_STAGE(PG8_SA(0, 1), a2 + hstep, voffA);
;             PG8_WAIT_V(8); PG8_WAIT_L(0); PG8_BAR; PG8_MMA(0, 0, At, B0); PG8_MMA(0, 1, At, B1); PG8_BAR; PG8_SCHED;
	s_setprio 1
	s_waitcnt lgkmcnt(0)
	v_mfma_f32_16x16x32_bf16 v[62:65], v[146:149], v[188:191], v[62:65]
	v_mfma_f32_16x16x32_bf16 v[58:61], v[164:167], v[188:191], v[58:61]
	v_mfma_f32_16x16x32_bf16 v[46:49], v[146:149], v[208:211], v[46:49]
	v_mfma_f32_16x16x32_bf16 v[42:45], v[164:167], v[208:211], v[42:45]
	v_mfma_f32_16x16x32_bf16 v[30:33], v[146:149], v[216:219], v[30:33]
	v_mfma_f32_16x16x32_bf16 v[26:29], v[164:167], v[216:219], v[26:29]
	v_mfma_f32_16x16x32_bf16 v[14:17], v[146:149], v[224:227], v[14:17]
	v_mfma_f32_16x16x32_bf16 v[10:13], v[164:167], v[224:227], v[10:13]
	v_mfma_f32_16x16x32_bf16 v[62:65], v[156:159], v[204:207], v[62:65]
	v_mfma_f32_16x16x32_bf16 v[58:61], v[168:171], v[204:207], v[58:61]
	v_mfma_f32_16x16x32_bf16 v[46:49], v[156:159], v[212:215], v[46:49]
	v_mfma_f32_16x16x32_bf16 v[42:45], v[168:171], v[212:215], v[42:45]
	v_mfma_f32_16x16x32_bf16 v[30:33], v[156:159], v[220:223], v[30:33]
	v_mfma_f32_16x16x32_bf16 v[26:29], v[168:171], v[220:223], v[26:29]
	v_mfma_f32_16x16x32_bf16 v[14:17], v[156:159], v[228:231], v[14:17]
	v_mfma_f32_16x16x32_bf16 v[10:13], v[168:171], v[228:231], v[10:13]
	s_setprio 0
	s_setprio 1
	v_mfma_f32_16x16x32_bf16 v[54:57], v[172:175], v[188:191], v[54:57]
	v_mfma_f32_16x16x32_bf16 v[50:53], v[180:183], v[188:191], v[50:53]
	v_mfma_f32_16x16x32_bf16 v[38:41], v[172:175], v[208:211], v[38:41]
	v_mfma_f32_16x16x32_bf16 v[34:37], v[180:183], v[208:211], v[34:37]
	v_mfma_f32_16x16x32_bf16 v[22:25], v[172:175], v[216:219], v[22:25]
	v_mfma_f32_16x16x32_bf16 v[18:21], v[180:183], v[216:219], v[18:21]
	v_mfma_f32_16x16x32_bf16 v[6:9], v[172:175], v[224:227], v[6:9]
	v_mfma_f32_16x16x32_bf16 v[2:5], v[180:183], v[224:227], v[2:5]
	v_mfma_f32_16x16x32_bf16 v[54:57], v[176:179], v[204:207], v[54:57]
	v_mfma_f32_16x16x32_bf16 v[50:53], v[184:187], v[204:207], v[50:53]
	v_mfma_f32_16x16x32_bf16 v[38:41], v[176:179], v[212:215], v[38:41]
	v_mfma_f32_16x16x32_bf16 v[34:37], v[184:187], v[212:215], v[34:37]
	v_mfma_f32_16x16x32_bf16 v[22:25], v[176:179], v[220:223], v[22:25]
	v_mfma_f32_16x16x32_bf16 v[18:21], v[184:187], v[220:223], v[18:21]
	v_mfma_f32_16x16x32_bf16 v[6:9], v[176:179], v[228:231], v[6:9]
	v_mfma_f32_16x16x32_bf16 v[2:5], v[184:187], v[228:231], v[2:5]
	s_setprio 0
	s_barrier
	s_add_i32 s88, 0, 0x18000
	v_add_u32_e32 v155, s88, v141
	s_add_i32 s89, 0, 0x1c000
	ds_read_b128 v[146:149], v155
	ds_read_b128 v[156:159], v155 offset:1024
	ds_read_b128 v[164:167], v155 offset:2048
	ds_read_b128 v[168:171], v155 offset:3072
	v_add_u32_e32 v155, s89, v141
	ds_read_b128 v[172:175], v155
	ds_read_b128 v[176:179], v155 offset:1024
	ds_read_b128 v[180:183], v155 offset:2048
	ds_read_b128 v[184:187], v155 offset:3072
	s_add_u32 s34, s74, 0x40000
	s_addc_u32 s35, s75, 0
	s_mov_b32 m0, s26
	v_lshl_add_u64 v[236:237], s[34:35], 0, v[138:139]
	ds_read_b128 v[188:191], v154 offset:32768
	ds_read_b128 v[204:207], v154 offset:33792
	ds_read_b128 v[208:211], v154 offset:34816
	ds_read_b128 v[212:215], v154 offset:35840
	ds_read_b128 v[216:219], v154 offset:36864
	ds_read_b128 v[220:223], v154 offset:37888
	ds_read_b128 v[224:227], v154 offset:38912
	ds_read_b128 v[228:231], v154 offset:39936
	global_load_lds_dwordx4 v[236:237], off
	v_lshl_add_u64 v[236:237], s[34:35], 0, v[134:135]
	s_mov_b32 m0, s27
	s_nop 0
	global_load_lds_dwordx4 v[236:237], off
	s_waitcnt vmcnt(8)
	s_waitcnt lgkmcnt(0)
	s_barrier
	s_setprio 1
	s_waitcnt lgkmcnt(0)
	v_mfma_f32_16x16x32_bf16 v[128:131], v[146:149], v[188:191], v[128:131]
	v_mfma_f32_16x16x32_bf16 v[124:127], v[164:167], v[188:191], v[124:127]
	v_mfma_f32_16x16x32_bf16 v[112:115], v[146:149], v[208:211], v[112:115]
	v_mfma_f32_16x16x32_bf16 v[108:111], v[164:167], v[208:211], v[108:111]
	v_mfma_f32_16x16x32_bf16 v[96:99], v[146:149], v[216:219], v[96:99]
	v_mfma_f32_16x16x32_bf16 v[92:95], v[164:167], v[216:219], v[92:95]
	v_mfma_f32_16x16x32_bf16 v[80:83], v[146:149], v[224:227], v[80:83]
	v_mfma_f32_16x16x32_bf16 v[76:79], v[164:167], v[224:227], v[76:79]
	v_mfma_f32_16x16x32_bf16 v[128:131], v[156:159], v[204:207], v[128:131]
	v_mfma_f32_16x16x32_bf16 v[124:127], v[168:171], v[204:207], v[124:127]
	v_mfma_f32_16x16x32_bf16 v[112:115], v[156:159], v[212:215], v[112:115]
	v_mfma_f32_16x16x32_bf16 v[108:111], v[168:171], v[212:215], v[108:111]
	v_mfma_f32_16x16x32_bf16 v[96:99], v[156:159], v[220:223], v[96:99]
	v_mfma_f32_16x16x32_bf16 v[92:95], v[168:171], v[220:223], v[92:95]
	v_mfma_f32_16x16x32_bf16 v[80:83], v[156:159], v[228:231], v[80:83]
	v_mfma_f32_16x16x32_bf16 v[76:79], v[168:171], v[228:231], v[76:79]
	s_setprio 0
	s_setprio 1
	v_mfma_f32_16x16x32_bf16 v[120:123], v[172:175], v[188:191], v[120:123]
	v_mfma_f32_16x16x32_bf16 v[116:119], v[180:183], v[188:191], v[116:119]
	v_mfma_f32_16x16x32_bf16 v[104:107], v[172:175], v[208:211], v[104:107]
	v_mfma_f32_16x16x32_bf16 v[100:103], v[180:183], v[208:211], v[100:103]
	v_mfma_f32_16x16x32_bf16 v[88:91], v[172:175], v[216:219], v[88:91]
	v_mfma_f32_16x16x32_bf16 v[84:87], v[180:183], v[216:219], v[84:87]
	v_mfma_f32_16x16x32_bf16 v[72:75], v[172:175], v[224:227], v[72:75]
	v_mfma_f32_16x16x32_bf16 v[68:71], v[180:183], v[224:227], v[68:71]
	v_mfma_f32_16x16x32_bf16 v[120:123], v[176:179], v[204:207], v[120:123]
	v_mfma_f32_16x16x32_bf16 v[116:119], v[184:187], v[204:207], v[116:119]
	v_mfma_f32_16x16x32_bf16 v[104:107], v[176:179], v[212:215], v[104:107]
	v_mfma_f32_16x16x32_bf16 v[100:103], v[184:187], v[212:215], v[100:103]
	v_mfma_f32_16x16x32_bf16 v[88:91], v[176:179], v[220:223], v[88:91]
	v_mfma_f32_16x16x32_bf16 v[84:87], v[184:187], v[220:223], v[84:87]
	v_mfma_f32_16x16x32_bf16 v[72:75], v[176:179], v[228:231], v[72:75]
	v_mfma_f32_16x16x32_bf16 v[68:71], v[184:187], v[228:231], v[68:71]
	s_setprio 0
	s_barrier
; #define PG8_STAGE(bufoff, gbase, voff) do { _Pragma("unroll") for (int _i = 0; _i < 2; ++_i) \
;         __builtin_amdgcn_global_load_lds((const unsigned*)((const char*)(gbase) + (voff)[_i]), (PG8_LAS unsigned*)(lds + (bufoff) + ldsw + _i * 8192), 16, 0, 0); } while (0)
; #define PG8_LDA(dst, b, h) do { _Pragma("unroll") for (int m = 0; m < 4; ++m) _Pragma("unroll") for (int k = 0; k < 2; ++k) dst[m][k] = *(const PG8_LAS bf16x8*)(lds + PG8_SA(b, h) + aoff + m * 2048 + k * 1024); } while (0)
; #define PG8_MMA(ai, bj, At, Bt) do { __builtin_amdgcn_s_setprio(1); _Pragma("unroll") for (int m = 0; m < 4; ++m) _Pragma("unroll") for (int n = 0; n < 2; ++n) _Pragma("unroll") for (int k = 0; k < 2; ++k) \
;         acc[ai][bj][m][n] = __builtin_amdgcn_mfma_f32_16x16x32_bf16(Bt[n][k], At[m][k], acc[ai][bj][m][n], 0, 0, 0); __builtin_amdgcn_s_setprio(0); } while (0)
; #define PG8_WAIT_V(n) asm volatile("s_waitcnt vmcnt(" #n ")" ::: "memory")
; #define PG8_WAIT_L(n) asm volatile("s_waitcnt lgkmcnt(" #n ")" ::: "memory")
; #define PG8_BAR __builtin_amdgcn_s_barrier()
; #define PG8_SCHED __builtin_amdgcn_sched_barrier(0)
; template <class Epi, class Sched, bool ALIGN_EPI = false, bool SP2 = false>
; __device__ __forceinline__ void gemm_phase(PG8_LAS unsigned char* lds, const Gemm g, const Sched& S, const Epi& E) {
;     ...
;             PG8_WAIT_V(8); PG8_WAIT_L(0); PG8_BAR; PG8_MMA(0, 0, At, B0); PG8_MMA(0, 1, At, B1); PG8_BAR; PG8_SCHED;
;             PG8_LDA(At, 1, 1); PG8_STAGE(PG8_SB(1, 0), b3, voffB); PG8_STAGE(PG8_SB(1, 1), b3 + hstepB, voffB); PG8_STAGE(PG8_SA(1, 0), a3, voffA);
;             PG8_WAIT_V(8); PG8_WAIT_L(0); PG8_BAR; PG8_MMA(1, 0, At, B0); PG8_MMA(1, 1, At, B1); PG8_BAR; PG8_SCHED;
	s_add_i32 s34, s88, s23
	v_lshl_add_u64 v[150:151], v[150:151], 0, s[52:53]
	s_mov_b32 m0, s34
	ds_read_b128 v[188:191], v154 offset:49152
	ds_read_b128 v[204:207], v154 offset:50176
	ds_read_b128 v[208:211], v154 offset:51200
	ds_read_b128 v[212:215], v154 offset:52224
	ds_read_b128 v[216:219], v154 offset:53248
	ds_read_b128 v[220:223], v154 offset:54272
	ds_read_b128 v[224:227], v154 offset:55296
	ds_read_b128 v[228:231], v154 offset:56320
	global_load_lds_dwordx4 v[150:151], off
	s_add_i32 m0, s34, 0x2000
	s_add_u32 s34, s38, 0x40080
	v_lshl_add_u64 v[150:151], v[192:193], 0, s[52:53]
	s_addc_u32 s35, s39, 0
	s_add_i32 s38, s89, s23
	global_load_lds_dwordx4 v[150:151], off
	v_lshl_add_u64 v[150:151], s[34:35], 0, v[136:137]
	s_mov_b32 m0, s38
	s_nop 0
	global_load_lds_dwordx4 v[150:151], off
	v_lshl_add_u64 v[150:151], s[34:35], 0, v[132:133]
	s_add_i32 m0, s38, 0x2000
	s_nop 0
	global_load_lds_dwordx4 v[150:151], off
	v_lshl_add_u64 v[150:151], v[232:233], 0, s[52:53]
	s_mov_b32 m0, s28
	s_nop 0
	global_load_lds_dwordx4 v[150:151], off
	v_lshl_add_u64 v[150:151], v[234:235], 0, s[52:53]
	s_mov_b32 m0, s29
	s_nop 0
	global_load_lds_dwordx4 v[150:151], off
	s_waitcnt vmcnt(8)
	s_waitcnt lgkmcnt(0)
	s_barrier
	s_setprio 1
	s_waitcnt lgkmcnt(0)
	v_mfma_f32_16x16x32_bf16 v[62:65], v[146:149], v[188:191], v[62:65]
	v_mfma_f32_16x16x32_bf16 v[58:61], v[164:167], v[188:191], v[58:61]
	v_mfma_f32_16x16x32_bf16 v[46:49], v[146:149], v[208:211], v[46:49]
	v_mfma_f32_16x16x32_bf16 v[42:45], v[164:167], v[208:211], v[42:45]
	v_mfma_f32_16x16x32_bf16 v[30:33], v[146:149], v[216:219], v[30:33]
	v_mfma_f32_16x16x32_bf16 v[26:29], v[164:167], v[216:219], v[26:29]
	v_mfma_f32_16x16x32_bf16 v[14:17], v[146:149], v[224:227], v[14:17]
	v_mfma_f32_16x16x32_bf16 v[10:13], v[164:167], v[224:227], v[10:13]
	v_mfma_f32_16x16x32_bf16 v[62:65], v[156:159], v[204:207], v[62:65]
	v_mfma_f32_16x16x32_bf16 v[58:61], v[168:171], v[204:207], v[58:61]
	v_mfma_f32_16x16x32_bf16 v[46:49], v[156:159], v[212:215], v[46:49]
	v_mfma_f32_16x16x32_bf16 v[42:45], v[168:171], v[212:215], v[42:45]
	v_mfma_f32_16x16x32_bf16 v[30:33], v[156:159], v[220:223], v[30:33]
	v_mfma_f32_16x16x32_bf16 v[26:29], v[168:171], v[220:223], v[26:29]
	v_mfma_f32_16x16x32_bf16 v[14:17], v[156:159], v[228:231], v[14:17]
	v_mfma_f32_16x16x32_bf16 v[10:13], v[168:171], v[228:231], v[10:13]
	s_setprio 0
	s_setprio 1
	v_mfma_f32_16x16x32_bf16 v[54:57], v[172:175], v[188:191], v[54:57]
	v_mfma_f32_16x16x32_bf16 v[50:53], v[180:183], v[188:191], v[50:53]
	v_mfma_f32_16x16x32_bf16 v[38:41], v[172:175], v[208:211], v[38:41]
	v_mfma_f32_16x16x32_bf16 v[34:37], v[180:183], v[208:211], v[34:37]
	v_mfma_f32_16x16x32_bf16 v[22:25], v[172:175], v[216:219], v[22:25]
	v_mfma_f32_16x16x32_bf16 v[18:21], v[180:183], v[216:219], v[18:21]
	v_mfma_f32_16x16x32_bf16 v[6:9], v[172:175], v[224:227], v[6:9]
	v_mfma_f32_16x16x32_bf16 v[2:5], v[180:183], v[224:227], v[2:5]
	v_mfma_f32_16x16x32_bf16 v[54:57], v[176:179], v[204:207], v[54:57]
	v_mfma_f32_16x16x32_bf16 v[50:53], v[184:187], v[204:207], v[50:53]
	v_mfma_f32_16x16x32_bf16 v[38:41], v[176:179], v[212:215], v[38:41]
	v_mfma_f32_16x16x32_bf16 v[34:37], v[184:187], v[212:215], v[34:37]
	v_mfma_f32_16x16x32_bf16 v[22:25], v[176:179], v[220:223], v[22:25]
	v_mfma_f32_16x16x32_bf16 v[18:21], v[184:187], v[220:223], v[18:21]
	v_mfma_f32_16x16x32_bf16 v[6:9], v[176:179], v[228:231], v[6:9]
	v_mfma_f32_16x16x32_bf16 v[2:5], v[184:187], v[228:231], v[2:5]
	s_setprio 0
	s_barrier
	s_add_i32 s31, s31, 2
	s_add_u32 s36, s36, 0x100
	s_addc_u32 s37, s37, 0
	s_add_u32 vcc_hi, vcc_hi, 0x100
	s_addc_u32 s30, s30, 0
	s_cmp_gt_u32 s31, 13
	s_cbranch_scc0 .LBB0_130
	s_cmp_lg_u32 s63, 3
	s_cbranch_scc1 .Lpa_early_skip
	v_readfirstlane_b32 s98, v0
	s_nop 3
	s_lshr_b32 s98, s98, 6
	s_cmp_lg_u32 s98, 0
	s_cbranch_scc1 .Lpa_early_skip
	s_mov_b64 exec, 1
	v_readlane_b32 s100, v242, 4
	s_nop 3
	s_lshr_b32 s100, s100, 6
	s_lshl_b32 s100, s100, 2
	v_mov_b32_e32 v250, s100
	s_cmp_ge_u32 s101, 5
	s_cselect_b32 s100, 2, 1
	v_mov_b32_e32 v251, s100
	v_readlane_b32 s98, v239, 63
	v_readlane_b32 s99, v241, 0
	s_nop 4
	global_store_dword v250, v251, s[98:99] offset:160 sc1
	s_mov_b64 exec, -1
.Lpa_early_skip:
	s_and_b64 vcc, exec, s[46:47]
	s_cbranch_vccz .LBB0_133
	s_barrier
